# GDN scan: LDS bank-conflict swizzle of the W/QI tiles (8-byte halves swapped on rows with bit 3 set, writers and operand reads agree)
# baseline (speedup 1.0000x reference)
; DI int otid() { int t = threadIdx.x; asm volatile("" : "+v"(t)); return t; }
; DI void gdn_scan_item(const P& p, int item, unsigned char* smem) {
;     ...
;     const int tid = otid(), w = tid >> 6, lane = tid & 63, l15 = lane & 15, g = lane >> 4, q4 = l15 >> 2, p4 = l15 & 3;
;     const int mt = w >> 1, nt = w & 1;
;     auto loadr = [&](GdnRegs& R, int c) {
;         if (c >= 36) return;
;         u32x4* rr = R.r;
; #pragma unroll
;         for (int k = 0; k < 2; ++k) {
;             const int e = tid + 512 * k, r = e >> 4, ch = e & 15; const size_t off = ((size_t)seq * PT + 64 * c + r) * 128 + 8 * ch;
;             rr[k] = *(const u32x4*)(W + off); rr[2 + k] = *(const u32x4*)(QI + off); rr[4 + k] = *(const u32x4*)(KO + off);
;         }
;         { const int r = tid >> 3, ch = tid & 7; rr[6] = *(const u32x4*)(AT + (((size_t)seq * 36 + c) * 64 + r) * 64 + 8 * ch); }
;         if (tid < 256) { const int r = tid >> 2, ch = tid & 3; rr[7] = __builtin_nontemporal_load((const u32x4*)(U + ((size_t)seq * PT + 64 * c + r) * 128 + 32 * cq + 8 * ch)); }
;     };
;     auto storel = [&](const GdnRegs& R, int buf) {
;         const u32x4* rr = R.r;
;         bf16_t* sW = (bf16_t*)(smem + buf * BUFB); bf16_t* sQI = sW + 64 * 136; bf16_t* sKO = sQI + 64 * 136; bf16_t* sAT = sKO + 64 * 136; bf16_t* sU = sAT + 64 * 72;
; #pragma unroll
;         for (int k = 0; k < 2; ++k) {
;             const int e = tid + 512 * k, r = e >> 4, ch = e & 15; const int off = r * 136 + 8 * ch;
;             *(u32x4*)(sW + off) = rr[k]; *(u32x4*)(sQI + off) = rr[2 + k]; *(u32x4*)(sKO + off) = rr[4 + k];
;         }
;         { const int r = tid >> 3, ch = tid & 7; *(u32x4*)(sAT + r * 72 + 8 * ch) = rr[6]; }
;         if (tid < 256) { const int r = tid >> 2, ch = tid & 3; *(u32x4*)(sU + r * 40 + 8 * ch) = rr[7]; }
;     };
;     u32x4* sBS = (u32x4*)(smem + 2 * BUFB + 5120 + 256);
;     f32x4 st[2];
;     st[0] = (f32x4){0.f, 0.f, 0.f, 0.f}; st[1] = (f32x4){0.f, 0.f, 0.f, 0.f};
;     sBS[(nt * 4 + mt) * 64 + lane] = (u32x4){0u, 0u, 0u, 0u};
;     if (tid < 36) sdec[tid] = DC[seq * 36 + tid];
;     const int sgn = dir ? -1 : 1;
.LBB0_499:
	s_or_b64 exec, exec, s[38:39]
	s_lshr_b32 s2, s22, 4
	s_and_b32 s3, s56, 3
	s_add_i32 s6, s57, 0x20800
	s_mul_i32 s2, s2, 0x900000
	s_add_u32 s2, s46, s2
	s_addc_u32 s4, s47, 0
	s_cmp_lt_u32 s22, 16
	s_cselect_b64 s[38:39], -1, 0
	s_lshl_b32 s5, s24, 8
	s_add_u32 s7, s2, s5
	s_movk_i32 s9, 0x88
	s_addc_u32 s8, s4, 0
	v_mad_u64_u32 v[120:121], s[4:5], v98, s9, v[132:133]
	v_mad_u64_u32 v[122:123], s[4:5], v100, s9, v[132:133]
	v_and_b32_e32 v108, 15, v96
	s_movk_i32 s4, 0x48
	v_lshrrev_b32_e32 v112, 4, v110
	v_mul_lo_u32 v114, v106, s4
	v_lshl_add_u32 v117, v110, 4, v111
	v_lshl_or_b32 v110, v97, 4, v108
	s_movk_i32 s4, 0x50
	v_lshlrev_b32_e32 v132, 5, v105
	v_lshlrev_b32_e32 v115, 4, v105
	v_mul_lo_u32 v106, v110, s4
	v_lshlrev_b32_e32 v124, 3, v112
	v_add_u32_e32 v105, s6, v132
	v_add3_u32 v123, v105, v106, v124
	v_lshlrev_b32_e32 v106, 2, v96
	v_bfe_u32 v113, v96, 2, 2
	v_and_b32_e32 v157, 12, v106
	v_lshlrev_b32_e32 v107, 13, v97
	v_lshlrev_b32_e32 v111, 2, v112
	v_lshl_add_u32 v112, v157, 1, v105
	v_or_b32_e32 v105, 4, v113
	v_lshl_or_b32 v107, v108, 9, v107
	s_lshl_b32 s2, s3, 11
	s_lshl_b32 s3, s3, 8
	v_or_b32_e32 v106, v124, v105
	v_sub_u32_e32 v109, 0, v107
	s_bitset1_b32 s3, 13
	v_mul_u32_u24_e32 v150, 0x50, v106
	v_or_b32_e32 v106, 32, v124
	v_or_b32_e32 v134, v124, v113
	v_or_b32_e32 v113, v106, v113
	v_or_b32_e32 v105, v106, v105
	s_add_u32 s4, s7, s26
	v_cndmask_b32_e64 v106, v109, v107, s[38:39]
	s_addc_u32 s5, s8, 0
	v_ashrrev_i32_e32 v107, 31, v106
	v_lshl_add_u64 v[106:107], v[106:107], 1, s[4:5]
	v_lshl_add_u64 v[106:107], v[106:107], 0, v[132:133]
	v_mov_b32_e32 v125, v133
	v_lshl_add_u64 v[106:107], v[106:107], 0, v[124:125]
	s_mov_b64 s[4:5], 0x5a3c000
	v_lshl_add_u64 v[126:127], v[106:107], 0, s[4:5]
	s_movk_i32 s4, 0xff40
	v_mul_lo_u32 v158, v110, s4
	s_movk_i32 s4, 0xc0
	s_add_i32 s24, s24, s22
	v_and_b32_e32 v96, 7, v96
	v_mul_lo_u32 v121, v110, s9
	v_lshlrev_b32_e32 v125, 5, v97
	v_mul_lo_u32 v159, v110, s4
	v_lshlrev_b32_e32 v97, 7, v110
	v_mad_u64_u32 v[102:103], s[4:5], s24, v181, v[102:103]
	v_lshlrev_b32_e32 v132, 4, v96
	v_readlane_b32 s8, v254, 26
	v_mul_u32_u24_e32 v152, 0x50, v105
	v_ashrrev_i32_e32 v105, 31, v104
	v_sub_u32_e32 v160, 0, v97
	v_lshl_add_u64 v[96:97], v[102:103], 0, v[132:133]
	v_readlane_b32 s9, v254, 27
	v_mul_u32_u24_e32 v135, 0x50, v134
	v_mul_u32_u24_e32 v151, 0x50, v113
	v_lshl_add_u64 v[142:143], s[8:9], 0, v[96:97]
	v_lshlrev_b64 v[96:97], 8, v[104:105]
	v_mad_u64_u32 v[96:97], s[4:5], s24, v182, v[96:97]
	s_lshl_b32 s4, s56, 3
	s_and_b32 s4, s4, 0xc0
	v_or_b32_e32 v96, s4, v96
	v_lshl_add_u64 v[96:97], v[118:119], 1, v[96:97]
	v_lshl_add_u64 v[144:145], s[8:9], 0, v[96:97]
	v_lshlrev_b64 v[96:97], 8, v[100:101]
	v_mad_u64_u32 v[96:97], s[4:5], s24, v182, v[96:97]
	v_lshlrev_b32_e32 v100, 4, v108
	v_or_b32_e32 v96, v96, v100
	v_lshl_add_u64 v[146:147], s[8:9], 0, v[96:97]
	v_lshlrev_b64 v[96:97], 8, v[98:99]
	v_mad_u64_u32 v[96:97], s[4:5], s24, v182, v[96:97]
	v_or_b32_e32 v96, v96, v100
	v_mul_u32_u24_e32 v106, 0x88, v134
	v_mul_u32_u24_e32 v107, 0x88, v113
	v_mul_lo_u32 v109, v104, 40
	v_lshl_add_u64 v[148:149], s[8:9], 0, v[96:97]
	v_mov_b32_e32 v96, 0
	s_mov_b32 s27, -3
	s_movk_i32 s22, 0x80
	s_movk_i32 s24, 0x87f
	v_lshlrev_b32_e32 v119, 1, v114
	v_lshlrev_b32_e32 v161, 1, v109
	v_lshlrev_b32_e32 v162, 1, v111
	v_lshlrev_b32_e32 v163, 1, v115
	v_add_u32_e32 v164, v112, v135
	v_add_u32_e32 v165, v112, v150
	v_add_u32_e32 v183, v112, v151
	v_add_u32_e32 v184, v112, v152
	v_lshlrev_b32_e32 v185, 1, v106
	v_lshlrev_b32_e32 v186, 1, v107
	v_mov_b32_e32 v97, v96
	v_mov_b32_e32 v98, v96
	v_mov_b32_e32 v99, v96
	v_mov_b32_e32 v100, v96
	v_mov_b32_e32 v101, v96
	v_mov_b32_e32 v102, v96
	v_mov_b32_e32 v103, v96
	v_readlane_b32 s10, v254, 28
	v_readlane_b32 s11, v254, 29
	v_cmp_gt_i32_e64 s[98:99], 36, v166
	s_nop 1
	s_and_saveexec_b64 s[100:101], s[98:99]
	s_waitcnt vmcnt(20)
	ds_write_b32 v217, v216
	s_mov_b64 exec, s[100:101]
	v_and_b32_e32 v218, 8, v166
	v_lshrrev_b32_e32 v219, 4, v166
	v_and_b32_e32 v219, 8, v219
	s_branch .LBB0_501

; DI void gdn_scan_item(const P& p, int item, unsigned char* smem) {
;     ...
;     auto loadr = [&](GdnRegs& R, int c) {
;         if (c >= 36) return;
;         u32x4* rr = R.r;
; #pragma unroll
;         for (int k = 0; k < 2; ++k) {
;             const int e = tid + 512 * k, r = e >> 4, ch = e & 15; const size_t off = ((size_t)seq * PT + 64 * c + r) * 128 + 8 * ch;
;             rr[k] = *(const u32x4*)(W + off); rr[2 + k] = *(const u32x4*)(QI + off); rr[4 + k] = *(const u32x4*)(KO + off);
;         }
;         { const int r = tid >> 3, ch = tid & 7; rr[6] = *(const u32x4*)(AT + (((size_t)seq * 36 + c) * 64 + r) * 64 + 8 * ch); }
;         if (tid < 256) { const int r = tid >> 2, ch = tid & 3; rr[7] = __builtin_nontemporal_load((const u32x4*)(U + ((size_t)seq * PT + 64 * c + r) * 128 + 32 * cq + 8 * ch)); }
;     };
;     auto storel = [&](const GdnRegs& R, int buf) {
;         const u32x4* rr = R.r;
;         bf16_t* sW = (bf16_t*)(smem + buf * BUFB); bf16_t* sQI = sW + 64 * 136; bf16_t* sKO = sQI + 64 * 136; bf16_t* sAT = sKO + 64 * 136; bf16_t* sU = sAT + 64 * 72;
; #pragma unroll
;         for (int k = 0; k < 2; ++k) {
;             const int e = tid + 512 * k, r = e >> 4, ch = e & 15; const int off = r * 136 + 8 * ch;
;             *(u32x4*)(sW + off) = rr[k]; *(u32x4*)(sQI + off) = rr[2 + k]; *(u32x4*)(sKO + off) = rr[4 + k];
;         }
;         { const int r = tid >> 3, ch = tid & 7; *(u32x4*)(sAT + r * 72 + 8 * ch) = rr[6]; }
;         if (tid < 256) { const int r = tid >> 2, ch = tid & 3; *(u32x4*)(sU + r * 40 + 8 * ch) = rr[7]; }
;     };
;     u32x4* sBS = (u32x4*)(smem + 2 * BUFB + 5120 + 256);
;     f32x4 st[2];
;     st[0] = (f32x4){0.f, 0.f, 0.f, 0.f}; st[1] = (f32x4){0.f, 0.f, 0.f, 0.f};
;     sBS[(nt * 4 + mt) * 64 + lane] = (u32x4){0u, 0u, 0u, 0u};
;     if (tid < 36) sdec[tid] = DC[seq * 36 + tid];
;     const int sgn = dir ? -1 : 1;
;     auto step = [&](GdnRegs& R, int c) {
;         storel(R, c & 1);
;         __syncthreads();
;         loadr(R, c + 3);
;         const bf16_t* sW = (const bf16_t*)(smem + (c & 1) * BUFB); const bf16_t* sQI = sW + 64 * 136; const bf16_t* sKO = sQI + 64 * 136; const bf16_t* sAT = sKO + 64 * 136; const bf16_t* sU = sAT + 64 * 72;
;         const float dec = sdec[c];
;         bf16x8 Bs[4];
; #pragma unroll
.LBB0_501:
	s_add_i32 s26, s27, 3
	s_bitcmp1_b32 s26, 0
	s_cselect_b32 s4, 0x10400, 0
	s_add_i32 s28, s57, s4
	v_lshlrev_b32_e32 v198, 1, v118
	v_lshl_add_u32 v190, v120, 1, s28
	v_lshl_add_u32 v192, v122, 1, s28
	v_add3_u32 v194, s28, v119, v116
	v_add3_u32 v191, s28, v161, v198
	s_waitcnt vmcnt(20)
	v_add_u32_e32 v216, v219, v190
	v_xor_b32_e32 v217, 8, v216
	ds_write_b64 v216, v[0:1]
	ds_write_b64 v217, v[2:3]
	s_waitcnt vmcnt(19)
	ds_write_b64 v216, v[4:5] offset:17408
	ds_write_b64 v217, v[6:7] offset:17408
	s_waitcnt vmcnt(18)
	ds_write_b128 v190, v[8:11] offset:34816
	s_waitcnt vmcnt(17)
	v_add_u32_e32 v216, v219, v192
	v_xor_b32_e32 v217, 8, v216
	ds_write_b64 v216, v[12:13]
	ds_write_b64 v217, v[14:15]
	s_waitcnt vmcnt(16)
	ds_write_b64 v216, v[16:17] offset:17408
	ds_write_b64 v217, v[18:19] offset:17408
	s_waitcnt vmcnt(15)
	ds_write_b128 v192, v[24:27] offset:34816
	s_waitcnt vmcnt(14)
	ds_write_b128 v194, v[36:39] offset:52224
	s_and_saveexec_b64 s[40:41], s[0:1]
	ds_write_b128 v191, v[20:23] offset:61440
	s_or_b64 exec, exec, s[40:41]
	s_cmp_gt_u32 s26, 32
	v_lshl_add_u64 v[154:155], v[148:149], 0, s[44:45]
	v_lshl_add_u64 v[152:153], v[146:147], 0, s[44:45]
	v_lshl_add_u64 v[150:151], v[142:143], 0, s[44:45]
	s_waitcnt lgkmcnt(0)
	s_barrier
	ds_read_b128 v[112:115], v117
	ds_read_b128 v[200:203], v117 offset:1024
	ds_read_b128 v[204:207], v117 offset:2048
	ds_read_b128 v[208:211], v117 offset:3072
	v_lshl_add_u32 v134, v121, 1, s28
	v_mov_b32_e32 v104, s21
	ds_read_b32 v132, v104
	v_add_u32_e32 v188, v134, v162
	v_xor_b32_e32 v188, v218, v188
	ds_read2_b64 v[224:227], v188 offset1:4
	ds_read2_b64 v[228:231], v188 offset0:8 offset1:12
	ds_read2_b64 v[232:235], v188 offset0:16 offset1:20
	ds_read2_b64 v[236:239], v188 offset0:24 offset1:28
	v_add_u32_e32 v134, v134, v158
	s_cbranch_scc1 .LBB0_507
	v_add_co_u32_e32 v0, vcc, 0x13f58000, v154
	s_nop 1
	v_addc_co_u32_e32 v1, vcc, 0, v155, vcc
	v_add_co_u32_e32 v4, vcc, 0x15158000, v154
	s_nop 1
	v_addc_co_u32_e32 v5, vcc, 0, v155, vcc
	v_add_co_u32_e32 v8, vcc, 0x16358000, v154
	global_load_dwordx4 v[0:3], v[0:1], off
	s_nop 0
	global_load_dwordx4 v[4:7], v[4:5], off
	v_addc_co_u32_e32 v9, vcc, 0, v155, vcc
	v_add_co_u32_e32 v12, vcc, 0x13f58000, v152
	global_load_dwordx4 v[8:11], v[8:9], off
	s_nop 0
	v_addc_co_u32_e32 v13, vcc, 0, v153, vcc
	v_add_co_u32_e32 v16, vcc, 0x15158000, v152
	s_nop 1
	v_addc_co_u32_e32 v17, vcc, 0, v153, vcc
	v_add_co_u32_e32 v24, vcc, 0x16358000, v152
	global_load_dwordx4 v[12:15], v[12:13], off
	s_nop 0
	global_load_dwordx4 v[16:19], v[16:17], off
	v_addc_co_u32_e32 v25, vcc, 0, v153, vcc
	v_add_co_u32_e32 v36, vcc, 0x17552000, v150
	global_load_dwordx4 v[24:27], v[24:25], off
	s_nop 0
	v_addc_co_u32_e32 v37, vcc, 0, v151, vcc
	global_load_dwordx4 v[36:39], v[36:37], off
	s_and_saveexec_b64 s[40:41], s[0:1]
	s_cbranch_execz .LBB0_506
	v_lshl_add_u64 v[20:21], v[144:145], 0, s[44:45]
	v_add_co_u32_e32 v20, vcc, 0x12d58000, v20
	s_nop 1
	v_addc_co_u32_e32 v21, vcc, 0, v21, vcc
	global_load_dwordx4 v[20:23], v[20:21], off nt

; DI float lo16(unsigned u) { return __uint_as_float(u << 16); }
; DI float hi16(unsigned u) { return __uint_as_float(u & 0xFFFF0000u); }
; DI bf16x8 tr2(const bf16_t* p0, const bf16_t* p1) { s16x4 a = trread(p0), b = trread(p1); return __builtin_shufflevector(a, b, 0, 1, 2, 3, 4, 5, 6, 7); }
; DI void gdn_scan_item(const P& p, int item, unsigned char* smem) {
;     ...
;     auto storel = [&](const GdnRegs& R, int buf) {
;         const u32x4* rr = R.r;
;         bf16_t* sW = (bf16_t*)(smem + buf * BUFB); bf16_t* sQI = sW + 64 * 136; bf16_t* sKO = sQI + 64 * 136; bf16_t* sAT = sKO + 64 * 136; bf16_t* sU = sAT + 64 * 72;
; #pragma unroll
;         for (int k = 0; k < 2; ++k) {
;             const int e = tid + 512 * k, r = e >> 4, ch = e & 15; const int off = r * 136 + 8 * ch;
;             *(u32x4*)(sW + off) = rr[k]; *(u32x4*)(sQI + off) = rr[2 + k]; *(u32x4*)(sKO + off) = rr[4 + k];
;         }
;         { const int r = tid >> 3, ch = tid & 7; *(u32x4*)(sAT + r * 72 + 8 * ch) = rr[6]; }
;         if (tid < 256) { const int r = tid >> 2, ch = tid & 3; *(u32x4*)(sU + r * 40 + 8 * ch) = rr[7]; }
;     ...
;         {
;             f32x4 acc = (f32x4){0.f, 0.f, 0.f, 0.f};
; #pragma unroll
;             for (int ks = 0; ks < 4; ++ks) { const bf16_t* r0 = sW + (16 * mt + l15) * 136 + 32 * ks + 4 * g; acc = mfma16(Bs[ks], ld4x2(r0, r0 + 16), acc); }
;             {
;                 const u32x2 uu = *(const u32x2*)(sU + (16 * mt + l15) * 40 + 16 * nt + 4 * g);
;                 u32x2 vv; vv.x = pk2(lo16(uu.x) - acc[0], hi16(uu.x) - acc[1]); vv.y = pk2(lo16(uu.y) - acc[2], hi16(uu.y) - acc[3]);
;                 *(u32x2*)(sVN + (16 * mt + l15) * 40 + 16 * nt + 4 * g) = vv;
;             }
;         }
;         __syncthreads();
;         bf16x8 Bv[2];
; #pragma unroll
;         for (int k2 = 0; k2 < 2; ++k2) Bv[k2] = tr2(sVN + (32 * k2 + 8 * g + q4) * 40 + 16 * nt + 4 * p4, sVN + (32 * k2 + 8 * g + 4 + q4) * 40 + 16 * nt + 4 * p4);
;         {
;             f32x4 acc = (f32x4){0.f, 0.f, 0.f, 0.f};
; #pragma unroll
;             for (int ks = 0; ks < 4; ++ks) { const bf16_t* r0 = sQI + (16 * mt + l15) * 136 + 32 * ks + 4 * g; acc = mfma16(Bs[ks], ld4x2(r0, r0 + 16), acc); }
; #pragma unroll
;             for (int k2 = 0; k2 < 2; ++k2) acc = mfma16(Bv[k2], ld8(sAT + (16 * mt + l15) * 72 + 32 * k2 + 8 * g), acc);
.LBB0_507:
	s_waitcnt lgkmcnt(3)
	v_mfma_f32_16x16x32_bf16 v[104:107], v[112:115], v[224:227], 0
	v_add3_u32 v195, v134, v163, v162
	ds_read_b64 v[240:241], v195 offset:61440
	v_add_u32_e32 v189, 0x4000, v188
	v_add_u32_e32 v134, v134, v159
	s_waitcnt lgkmcnt(3)
	v_mfma_f32_16x16x32_bf16 v[104:107], v[200:203], v[228:231], v[104:107]
	v_lshlrev_b32_e32 v199, 1, v124
	v_add3_u32 v196, v134, v160, v199
	s_waitcnt lgkmcnt(2)
	v_mfma_f32_16x16x32_bf16 v[104:107], v[204:207], v[232:235], v[104:107]
	s_mov_b64 s[42:43], -1
	s_cmp_gt_u32 s26, 3
	s_waitcnt lgkmcnt(1)
	v_mfma_f32_16x16x32_bf16 v[104:107], v[208:211], v[236:239], v[104:107]
	s_waitcnt lgkmcnt(0)
	v_lshlrev_b32_e32 v110, 16, v240
	v_and_b32_e32 v108, 0xffff0000, v240
	s_nop 3
	s_nop 0
	v_sub_f32_e32 v104, v110, v104
	v_sub_f32_e32 v105, v108, v105
	v_cvt_pk_bf16_f32 v104, v104, v105
	v_lshlrev_b32_e32 v105, 16, v241
	v_sub_f32_e32 v105, v105, v106
	v_and_b32_e32 v106, 0xffff0000, v241
	v_sub_f32_e32 v106, v106, v107
	v_cvt_pk_bf16_f32 v105, v105, v106
	ds_write_b64 v123, v[104:105]
	s_waitcnt lgkmcnt(0)
	s_barrier
	v_mov_b32_e32 v212, s27
	v_and_b32_e32 v212, 1, v212
	v_mul_u32_u24_e32 v212, 0x10400, v212
	v_add_u32_e32 v212, s57, v212
	v_lshl_add_u32 v213, v120, 1, v212
	v_lshl_add_u32 v214, v122, 1, v212
	v_add3_u32 v215, v212, v119, v116
	ds_read_b64_tr_b16 v[108:109], v164
	ds_read_b64_tr_b16 v[110:111], v165
	ds_read_b64_tr_b16 v[104:105], v183
	ds_read_b64_tr_b16 v[106:107], v184
	ds_read2_b64 v[224:227], v189 offset0:128 offset1:132
	ds_read2_b64 v[228:231], v189 offset0:136 offset1:140
	ds_read2_b64 v[232:235], v189 offset0:144 offset1:148
	ds_read2_b64 v[236:239], v189 offset0:152 offset1:156
	ds_read_b128 v[240:243], v196 offset:52224
	ds_read_b128 v[244:247], v196 offset:52288
	s_waitcnt lgkmcnt(5)
	v_mfma_f32_16x16x32_bf16 v[112:115], v[112:115], v[224:227], 0
	s_waitcnt vmcnt(14)
	v_add_u32_e32 v216, v219, v213
	v_xor_b32_e32 v217, 8, v216
	ds_write_b64 v216, v[28:29]
	ds_write_b64 v217, v[30:31]
	s_waitcnt lgkmcnt(6)
	v_mfma_f32_16x16x32_bf16 v[112:115], v[200:203], v[228:231], v[112:115]
	s_waitcnt vmcnt(13)
	ds_write_b64 v216, v[32:33] offset:17408
	ds_write_b64 v217, v[34:35] offset:17408
	s_waitcnt lgkmcnt(7)
	v_mfma_f32_16x16x32_bf16 v[112:115], v[204:207], v[232:235], v[112:115]
	s_waitcnt vmcnt(12)
	ds_write_b128 v213, v[40:43] offset:34816
	s_waitcnt lgkmcnt(7)
	v_mfma_f32_16x16x32_bf16 v[112:115], v[208:211], v[236:239], v[112:115]
	s_waitcnt vmcnt(11)
	v_add_u32_e32 v216, v219, v214
	v_xor_b32_e32 v217, 8, v216
	ds_write_b64 v216, v[48:49]
	ds_write_b64 v217, v[50:51]
	s_waitcnt lgkmcnt(8)
	v_mfma_f32_16x16x32_bf16 v[112:115], v[108:111], v[240:243], v[112:115]
	s_waitcnt vmcnt(10)
	ds_write_b64 v216, v[52:53] offset:17408
	ds_write_b64 v217, v[54:55] offset:17408
	s_waitcnt lgkmcnt(9)
	v_mfma_f32_16x16x32_bf16 v[112:115], v[104:107], v[244:247], v[112:115]
	s_cbranch_scc0 .LBB0_509
	s_add_i32 s6, s22, 0xfffffe80
	s_add_i32 s7, s24, 0x80
	s_and_b64 s[4:5], s[38:39], exec
	s_cselect_b32 s4, s6, s7
	s_add_i32 s40, s4, s2
	s_mov_b64 s[42:43], 0

; DI bf16x8 tr2(const bf16_t* p0, const bf16_t* p1) { s16x4 a = trread(p0), b = trread(p1); return __builtin_shufflevector(a, b, 0, 1, 2, 3, 4, 5, 6, 7); }
; DI f32x4 mfma16(bf16x8 a, bf16x8 b, f32x4 c) { return __builtin_amdgcn_mfma_f32_16x16x32_bf16(a, b, c, 0, 0, 0); }
; DI void gdn_scan_item(const P& p, int item, unsigned char* smem) {
;     ...
;     auto storel = [&](const GdnRegs& R, int buf) {
;         const u32x4* rr = R.r;
;         bf16_t* sW = (bf16_t*)(smem + buf * BUFB); bf16_t* sQI = sW + 64 * 136; bf16_t* sKO = sQI + 64 * 136; bf16_t* sAT = sKO + 64 * 136; bf16_t* sU = sAT + 64 * 72;
; #pragma unroll
;         for (int k = 0; k < 2; ++k) {
;             const int e = tid + 512 * k, r = e >> 4, ch = e & 15; const int off = r * 136 + 8 * ch;
;             *(u32x4*)(sW + off) = rr[k]; *(u32x4*)(sQI + off) = rr[2 + k]; *(u32x4*)(sKO + off) = rr[4 + k];
;         }
;         { const int r = tid >> 3, ch = tid & 7; *(u32x4*)(sAT + r * 72 + 8 * ch) = rr[6]; }
;         if (tid < 256) { const int r = tid >> 2, ch = tid & 3; *(u32x4*)(sU + r * 40 + 8 * ch) = rr[7]; }
;     ...
; #pragma unroll
;             for (int k2 = 0; k2 < 2; ++k2) acc = mfma16(Bv[k2], ld8(sAT + (16 * mt + l15) * 72 + 32 * k2 + 8 * g), acc);
;             bf16_t* ob = OG + (size_t)prow(b, dir, 64 * c) * 512 + 128 * h + 32 * cq;
;             u32x2 ov; ov.x = pk2(acc[0], acc[1]); ov.y = pk2(acc[2], acc[3]);
;             *(u32x2*)(ob + sgn * ((16 * mt + l15) * 512) + 16 * nt + 4 * g) = ov;
;         }
; #pragma unroll
;         for (int j = 0; j < 2; ++j) {
;             const int dt = 2 * mt + j;
;             st[j] *= dec;
; #pragma unroll
;             for (int k2 = 0; k2 < 2; ++k2) {
;                 const bf16x8 ak = tr2(sKO + (32 * k2 + 8 * g + q4) * 136 + 16 * dt + 4 * p4, sKO + (32 * k2 + 8 * g + 4 + q4) * 136 + 16 * dt + 4 * p4);
;                 st[j] = mfma16(ak, Bv[k2], st[j]);
;             }
;         }
;         sBS[(nt * 4 + mt) * 64 + lane] = __builtin_bit_cast(u32x4, packacc(st[0], st[1]));
.LBB0_511:
	v_lshl_add_u32 v134, v125, 1, s28
	v_lshlrev_b32_e32 v197, 1, v157
	v_add3_u32 v187, v134, v185, v197
	ds_read_b64_tr_b16 v[226:227], v187 offset:35904
	ds_read_b64_tr_b16 v[224:225], v187 offset:34816
	ds_read_b64_tr_b16 v[230:231], v187 offset:44608
	ds_read_b64_tr_b16 v[234:235], v187 offset:35936
	ds_read_b64_tr_b16 v[232:233], v187 offset:34848
	ds_read_b64_tr_b16 v[238:239], v187 offset:44640
	v_add3_u32 v193, v134, v186, v197
	ds_read_b64_tr_b16 v[228:229], v193 offset:34816
	ds_read_b64_tr_b16 v[236:237], v193 offset:34848
	v_pk_mul_f32 v[98:99], v[98:99], v[132:133] op_sel_hi:[1,0]
	v_pk_mul_f32 v[96:97], v[96:97], v[132:133] op_sel_hi:[1,0]
	v_pk_mul_f32 v[102:103], v[102:103], v[132:133] op_sel_hi:[1,0]
	v_pk_mul_f32 v[100:101], v[100:101], v[132:133] op_sel_hi:[1,0]
	s_waitcnt lgkmcnt(6)
	v_mfma_f32_16x16x32_bf16 v[96:99], v[224:227], v[108:111], v[96:99]
	s_waitcnt vmcnt(9)
	ds_write_b128 v214, v[64:67] offset:34816
	s_ashr_i32 s41, s40, 31
	s_lshl_b64 s[4:5], s[40:41], 10
	s_waitcnt lgkmcnt(4)
	v_mfma_f32_16x16x32_bf16 v[100:103], v[232:235], v[108:111], v[100:103]
	s_waitcnt vmcnt(3)
	ds_write_b128 v215, v[72:75] offset:52224
	s_bitcmp1_b32 s27, 0
	v_lshl_add_u64 v[108:109], v[126:127], 0, s[4:5]
	s_cselect_b32 s4, 0x10400, 0
	s_waitcnt lgkmcnt(3)
	v_mfma_f32_16x16x32_bf16 v[96:99], v[228:231], v[104:107], v[96:99]
	s_add_i32 s27, s57, s4
	v_cvt_pk_bf16_f32 v112, v112, v113
	v_cvt_pk_bf16_f32 v113, v114, v115
	s_waitcnt lgkmcnt(2)
	v_mfma_f32_16x16x32_bf16 v[100:103], v[236:239], v[104:107], v[100:103]
	global_store_dwordx2 v[108:109], v[112:113], off
	s_nop 1
	v_cvt_pk_bf16_f32 v104, v96, v97
	v_cvt_pk_bf16_f32 v105, v98, v99
	s_nop 2
	v_cvt_pk_bf16_f32 v106, v100, v101
	v_cvt_pk_bf16_f32 v107, v102, v103
	ds_write_b128 v156, v[104:107]
	s_waitcnt lgkmcnt(0)
	s_and_saveexec_b64 s[40:41], s[0:1]
	v_add3_u32 v104, s27, v161, v198
	ds_write_b128 v104, v[44:47] offset:61440
	s_or_b64 exec, exec, s[40:41]
	s_cmp_gt_u32 s26, 31
	v_readlane_b32 s12, v254, 56
	s_waitcnt lgkmcnt(0)
	s_barrier
	ds_read_b128 v[110:113], v117
	ds_read_b128 v[200:203], v117 offset:1024
	ds_read_b128 v[204:207], v117 offset:2048
	ds_read_b128 v[208:211], v117 offset:3072
	v_lshl_add_u32 v109, v121, 1, s27
	v_mov_b32_e32 v104, s21
	ds_read_b32 v108, v104 offset:4
	v_add_u32_e32 v132, v109, v162
	v_xor_b32_e32 v132, v218, v132
	ds_read2_b64 v[224:227], v132 offset1:4
	ds_read2_b64 v[228:231], v132 offset0:8 offset1:12
	ds_read2_b64 v[236:239], v132 offset0:16 offset1:20
	ds_read2_b64 v[240:243], v132 offset0:24 offset1:28
	v_add_u32_e32 v109, v109, v158
	v_readlane_b32 s13, v254, 57
	s_cbranch_scc1 .LBB0_517
	v_add_co_u32_e32 v28, vcc, 0x13f5c000, v154
	s_nop 1
	v_addc_co_u32_e32 v29, vcc, 0, v155, vcc
	v_add_co_u32_e32 v32, vcc, 0x1515c000, v154
	s_nop 1
	v_addc_co_u32_e32 v33, vcc, 0, v155, vcc
	v_add_co_u32_e32 v40, vcc, 0x1635c000, v154
	global_load_dwordx4 v[28:31], v[28:29], off
	s_nop 0
	global_load_dwordx4 v[32:35], v[32:33], off
	v_addc_co_u32_e32 v41, vcc, 0, v155, vcc
	v_add_co_u32_e32 v48, vcc, 0x13f5c000, v152
	global_load_dwordx4 v[40:43], v[40:41], off
	s_nop 0
	v_addc_co_u32_e32 v49, vcc, 0, v153, vcc
	v_add_co_u32_e32 v52, vcc, 0x1515c000, v152
	s_nop 1
	v_addc_co_u32_e32 v53, vcc, 0, v153, vcc
	v_add_co_u32_e32 v64, vcc, 0x1635c000, v152
	global_load_dwordx4 v[48:51], v[48:49], off
	s_nop 0
	global_load_dwordx4 v[52:55], v[52:53], off
	v_addc_co_u32_e32 v65, vcc, 0, v153, vcc
	v_add_co_u32_e32 v72, vcc, 0x17554000, v150
	global_load_dwordx4 v[64:67], v[64:65], off
	s_nop 0
	v_addc_co_u32_e32 v73, vcc, 0, v151, vcc
	global_load_dwordx4 v[72:75], v[72:73], off
	s_and_saveexec_b64 s[40:41], s[0:1]
	s_cbranch_execz .LBB0_516
	v_lshl_add_u64 v[44:45], v[144:145], 0, s[44:45]
	v_add_co_u32_e32 v44, vcc, 0x12d5c000, v44
	s_nop 1
	v_addc_co_u32_e32 v45, vcc, 0, v45, vcc
	global_load_dwordx4 v[44:47], v[44:45], off nt

; DI void gdn_scan_item(const P& p, int item, unsigned char* smem) {
;     ...
;     auto storel = [&](const GdnRegs& R, int buf) {
;         const u32x4* rr = R.r;
;         bf16_t* sW = (bf16_t*)(smem + buf * BUFB); bf16_t* sQI = sW + 64 * 136; bf16_t* sKO = sQI + 64 * 136; bf16_t* sAT = sKO + 64 * 136; bf16_t* sU = sAT + 64 * 72;
; #pragma unroll
;         for (int k = 0; k < 2; ++k) {
;     ...
;         {
;             f32x4 acc = (f32x4){0.f, 0.f, 0.f, 0.f};
; #pragma unroll
;             for (int ks = 0; ks < 4; ++ks) { const bf16_t* r0 = sW + (16 * mt + l15) * 136 + 32 * ks + 4 * g; acc = mfma16(Bs[ks], ld4x2(r0, r0 + 16), acc); }
;             {
;                 const u32x2 uu = *(const u32x2*)(sU + (16 * mt + l15) * 40 + 16 * nt + 4 * g);
;                 u32x2 vv; vv.x = pk2(lo16(uu.x) - acc[0], hi16(uu.x) - acc[1]); vv.y = pk2(lo16(uu.y) - acc[2], hi16(uu.y) - acc[3]);
;                 *(u32x2*)(sVN + (16 * mt + l15) * 40 + 16 * nt + 4 * g) = vv;
;             }
;         }
;         __syncthreads();
;         bf16x8 Bv[2];
; #pragma unroll
;         for (int k2 = 0; k2 < 2; ++k2) Bv[k2] = tr2(sVN + (32 * k2 + 8 * g + q4) * 40 + 16 * nt + 4 * p4, sVN + (32 * k2 + 8 * g + 4 + q4) * 40 + 16 * nt + 4 * p4);
;         {
;             f32x4 acc = (f32x4){0.f, 0.f, 0.f, 0.f};
; #pragma unroll
;             for (int ks = 0; ks < 4; ++ks) { const bf16_t* r0 = sQI + (16 * mt + l15) * 136 + 32 * ks + 4 * g; acc = mfma16(Bs[ks], ld4x2(r0, r0 + 16), acc); }
; #pragma unroll
;             for (int k2 = 0; k2 < 2; ++k2) acc = mfma16(Bv[k2], ld8(sAT + (16 * mt + l15) * 72 + 32 * k2 + 8 * g), acc);
;             bf16_t* ob = OG + (size_t)prow(b, dir, 64 * c) * 512 + 128 * h + 32 * cq;
;             u32x2 ov; ov.x = pk2(acc[0], acc[1]); ov.y = pk2(acc[2], acc[3]);
;             *(u32x2*)(ob + sgn * ((16 * mt + l15) * 512) + 16 * nt + 4 * g) = ov;
;         }
; #pragma unroll
;         for (int j = 0; j < 2; ++j) {
;             const int dt = 2 * mt + j;
;             st[j] *= dec;
; #pragma unroll
;             for (int k2 = 0; k2 < 2; ++k2) {
;                 const bf16x8 ak = tr2(sKO + (32 * k2 + 8 * g + q4) * 136 + 16 * dt + 4 * p4, sKO + (32 * k2 + 8 * g + 4 + q4) * 136 + 16 * dt + 4 * p4);
;                 st[j] = mfma16(ak, Bv[k2], st[j]);
;             }
;         }
;         sBS[(nt * 4 + mt) * 64 + lane] = __builtin_bit_cast(u32x4, packacc(st[0], st[1]));
.LBB0_517:
	s_waitcnt lgkmcnt(3)
	v_mfma_f32_16x16x32_bf16 v[104:107], v[110:113], v[224:227], 0
	v_add3_u32 v114, v109, v163, v162
	ds_read_b64 v[232:233], v114 offset:61440
	v_add_u32_e32 v109, v109, v159
	s_waitcnt lgkmcnt(3)
	v_mfma_f32_16x16x32_bf16 v[104:107], v[200:203], v[228:231], v[104:107]
	v_add3_u32 v109, v109, v160, v199
	s_waitcnt lgkmcnt(0)
	v_lshlrev_b32_e32 v134, 16, v232
	v_mfma_f32_16x16x32_bf16 v[104:107], v[204:207], v[236:239], v[104:107]
	v_and_b32_e32 v114, 0xffff0000, v232
	s_sub_i32 s4, s22, 64
	v_mfma_f32_16x16x32_bf16 v[104:107], v[208:211], v[240:243], v[104:107]
	s_add_i32 s5, s22, 0xfffffec0
	s_cmp_lt_u32 s26, 3
	s_movk_i32 s6, 0x8ff
	s_nop 4
	v_sub_f32_e32 v104, v134, v104
	v_sub_f32_e32 v105, v114, v105
	v_cvt_pk_bf16_f32 v104, v104, v105
	v_lshlrev_b32_e32 v105, 16, v233
	v_sub_f32_e32 v105, v105, v106
	v_and_b32_e32 v106, 0xffff0000, v233
	v_sub_f32_e32 v106, v106, v107
	v_cvt_pk_bf16_f32 v105, v105, v106
	v_add_u32_e32 v114, 0x4000, v132
	ds_write_b64 v123, v[104:105]
	s_waitcnt lgkmcnt(0)
	s_barrier
	ds_read_b64_tr_b16 v[224:225], v164
	ds_read_b64_tr_b16 v[226:227], v165
	ds_read_b64_tr_b16 v[228:229], v183
	ds_read_b64_tr_b16 v[230:231], v184
	ds_read2_b64 v[232:235], v114 offset0:128 offset1:132
	ds_read2_b64 v[236:239], v114 offset0:136 offset1:140
	ds_read2_b64 v[240:243], v114 offset0:144 offset1:148
	ds_read2_b64 v[244:247], v114 offset0:152 offset1:156
	ds_read_b128 v[248:251], v109 offset:52224
	s_waitcnt lgkmcnt(4)
	v_mfma_f32_16x16x32_bf16 v[110:113], v[110:113], v[232:235], 0
	ds_read_b128 v[232:235], v109 offset:52288
	s_waitcnt vmcnt(8)
	v_add_u32_e32 v216, v219, v190
	v_xor_b32_e32 v217, 8, v216
	ds_write_b64 v216, v[56:57]
	ds_write_b64 v217, v[58:59]
	s_cselect_b32 s6, 0xff, s6
	s_cselect_b32 s7, s4, s5
	s_waitcnt lgkmcnt(6)
	v_mfma_f32_16x16x32_bf16 v[110:113], v[200:203], v[236:239], v[110:113]
	s_waitcnt vmcnt(7)
	ds_write_b64 v216, v[60:61] offset:17408
	ds_write_b64 v217, v[62:63] offset:17408
	s_cselect_b32 s8, s3, s2
	s_add_i32 s4, s6, s24
	s_waitcnt lgkmcnt(7)
	v_mfma_f32_16x16x32_bf16 v[110:113], v[204:207], v[240:243], v[110:113]
	s_waitcnt vmcnt(6)
	ds_write_b128 v190, v[68:71] offset:34816
	s_add_i32 s6, s4, 0xfffff741
	s_and_b64 s[4:5], s[38:39], exec
	s_waitcnt lgkmcnt(7)
	v_mfma_f32_16x16x32_bf16 v[110:113], v[208:211], v[244:247], v[110:113]
	s_waitcnt vmcnt(5)
	v_add_u32_e32 v216, v219, v192
	v_xor_b32_e32 v217, 8, v216
	ds_write_b64 v216, v[76:77]
	ds_write_b64 v217, v[78:79]
	s_cselect_b32 s4, s7, s6
	s_add_i32 s4, s4, s8
	s_waitcnt lgkmcnt(8)
	v_mfma_f32_16x16x32_bf16 v[110:113], v[224:227], v[248:251], v[110:113]
	s_waitcnt vmcnt(4)
	ds_write_b64 v216, v[80:81] offset:17408
	ds_write_b64 v217, v[82:83] offset:17408
	s_ashr_i32 s5, s4, 31
	s_lshl_b64 s[4:5], s[4:5], 10
	s_waitcnt lgkmcnt(9)
	v_mfma_f32_16x16x32_bf16 v[110:113], v[228:231], v[232:235], v[110:113]
	v_mul_f32_e64 v98, v98, v108
	v_mul_f32_e64 v99, v99, v108
	v_pk_mul_f32 v[96:97], v[96:97], v[108:109] op_sel_hi:[1,0]
	v_lshl_add_u32 v109, v125, 1, s27
	s_nop 3
	v_cvt_pk_bf16_f32 v110, v110, v111
	v_cvt_pk_bf16_f32 v111, v112, v113
	v_lshl_add_u64 v[112:113], v[126:127], 0, s[4:5]
	global_store_dwordx2 v[112:113], v[110:111], off
	v_add3_u32 v114, v109, v185, v197
	ds_read_b64_tr_b16 v[238:239], v114 offset:35904
	ds_read_b64_tr_b16 v[236:237], v114 offset:34816
	ds_read_b64_tr_b16 v[240:241], v114 offset:34848
	ds_read_b64_tr_b16 v[246:247], v114 offset:44608
	ds_read_b64_tr_b16 v[242:243], v114 offset:35936
	ds_read_b64_tr_b16 v[250:251], v114 offset:44640
	s_waitcnt lgkmcnt(4)
	v_mfma_f32_16x16x32_bf16 v[96:99], v[236:239], v[224:227], v[96:99]
	s_waitcnt vmcnt(3)
	ds_write_b128 v192, v[84:87] offset:34816
	v_add3_u32 v109, v109, v186, v197
	ds_read_b64_tr_b16 v[244:245], v109 offset:34816
	ds_read_b64_tr_b16 v[248:249], v109 offset:34848
	v_pk_mul_f32 v[102:103], v[102:103], v[108:109] op_sel_hi:[1,0]
	v_pk_mul_f32 v[100:101], v[100:101], v[108:109] op_sel_hi:[1,0]
	s_waitcnt lgkmcnt(1)
	v_mfma_f32_16x16x32_bf16 v[96:99], v[244:247], v[228:231], v[96:99]
	s_waitcnt vmcnt(2)
	ds_write_b128 v194, v[92:95] offset:52224
	v_mfma_f32_16x16x32_bf16 v[100:103], v[240:243], v[224:227], v[100:103]
	s_waitcnt lgkmcnt(1)
	v_mfma_f32_16x16x32_bf16 v[100:103], v[248:251], v[228:231], v[100:103]
	s_nop 3
	s_nop 0
	v_cvt_pk_bf16_f32 v104, v96, v97
	v_cvt_pk_bf16_f32 v105, v98, v99
	s_nop 1
	v_cvt_pk_bf16_f32 v106, v100, v101
	v_cvt_pk_bf16_f32 v107, v102, v103
	ds_write_b128 v156, v[104:107]
	s_waitcnt lgkmcnt(0)
	s_and_saveexec_b64 s[40:41], s[0:1]
	ds_write_b128 v191, v[88:91] offset:61440
	s_or_b64 exec, exec, s[40:41]
	s_cmp_gt_u32 s26, 30
	s_waitcnt lgkmcnt(0)
	s_barrier
	ds_read_b128 v[112:115], v117
	ds_read_b128 v[248:251], v117 offset:1024
	ds_read_b128 v[198:201], v117 offset:2048
	ds_read_b128 v[202:205], v117 offset:3072
	ds_read2_b64 v[224:227], v188 offset1:4
	ds_read2_b64 v[228:231], v188 offset0:8 offset1:12
	ds_read2_b64 v[232:235], v188 offset0:16 offset1:20
	ds_read2_b64 v[236:239], v188 offset0:24 offset1:28
	ds_read_b64 v[240:241], v195 offset:61440
	v_mov_b32_e32 v104, s21
	ds_read_b32 v132, v104 offset:8
	s_cbranch_scc1 .LBB0_523
	v_add_co_u32_e32 v56, vcc, 0x13f60000, v154
	s_nop 1
	v_addc_co_u32_e32 v57, vcc, 0, v155, vcc
	v_add_co_u32_e32 v60, vcc, 0x15160000, v154
	s_nop 1
	v_addc_co_u32_e32 v61, vcc, 0, v155, vcc
	v_add_co_u32_e32 v68, vcc, 0x16360000, v154
	global_load_dwordx4 v[56:59], v[56:57], off
	s_nop 0
	global_load_dwordx4 v[60:63], v[60:61], off
	v_addc_co_u32_e32 v69, vcc, 0, v155, vcc
	v_add_co_u32_e32 v76, vcc, 0x13f60000, v152
	global_load_dwordx4 v[68:71], v[68:69], off
	s_nop 0
	v_addc_co_u32_e32 v77, vcc, 0, v153, vcc
	v_add_co_u32_e32 v80, vcc, 0x15160000, v152
	s_nop 1
	v_addc_co_u32_e32 v81, vcc, 0, v153, vcc
	v_add_co_u32_e32 v84, vcc, 0x16360000, v152
	global_load_dwordx4 v[76:79], v[76:77], off
	s_nop 0
	global_load_dwordx4 v[80:83], v[80:81], off
	v_addc_co_u32_e32 v85, vcc, 0, v153, vcc
	v_add_co_u32_e32 v92, vcc, 0x17556000, v150
	global_load_dwordx4 v[84:87], v[84:85], off
	s_nop 0
	v_addc_co_u32_e32 v93, vcc, 0, v151, vcc
	global_load_dwordx4 v[92:95], v[92:93], off
	s_and_saveexec_b64 s[40:41], s[0:1]
	s_cbranch_execz .LBB0_522
	v_lshl_add_u64 v[88:89], v[144:145], 0, s[44:45]
	v_add_co_u32_e32 v88, vcc, 0x12d60000, v88
	s_nop 1
	v_addc_co_u32_e32 v89, vcc, 0, v89, vcc
	global_load_dwordx4 v[88:91], v[88:89], off nt
